# hand-written attention key loop: maps interleaved sharing V fragments, persistent C-init reference, lazy rescale on running row sums
# speedup vs baseline: 1.0613x; 1.0569x over previous
.LBB0_765:
	s_mul_i32 s0, s36, 0x1dc0000
	s_mul_hi_i32 s1, s36, 0x1dc0000
	s_add_u32 s0, s24, s0
	s_addc_u32 s1, s25, s1
	s_lshl_b32 s6, s4, 6
	s_and_b32 s33, s6, 0xc0
	s_lshl_b32 s22, s33, 1
	s_cmp_lt_u32 s5, 2
	v_mov_b32_e32 v18, v222
	s_cselect_b32 s38, 4, 0x44
	v_lshlrev_b32_e32 v0, 4, v18
	s_add_u32 s6, s0, s22
	v_and_b32_e32 v4, 0x70, v0
	v_mov_b32_e32 v5, v3
	s_addc_u32 s7, s1, 0
	v_lshl_add_u64 v[0:1], s[6:7], 0, v[4:5]
	s_mov_b64 s[6:7], 0x1600
	v_ashrrev_i32_e32 v19, 3, v18
	v_lshl_add_u64 v[6:7], v[0:1], 0, s[6:7]
	s_mov_b64 s[6:7], 0x1800
	v_lshl_add_u64 v[0:1], v[0:1], 0, s[6:7]
	v_add_u32_e32 v2, 32, v19
	v_mad_i64_i32 v[10:11], s[6:7], v19, s48, v[0:1]
	v_mad_i64_i32 v[12:13], s[6:7], v2, s48, v[0:1]
	v_ashrrev_i32_e32 v0, 1, v18
	v_and_b32_e32 v0, 0xffffffe0, v0
	v_and_b32_e32 v5, 31, v18
	v_lshl_add_u32 v0, s5, 7, v0
	v_or_b32_e32 v148, v0, v5
	v_mov_b64_e32 v[0:1], s[0:1]
	v_bfe_u32 v219, v18, 5, 1
	v_mad_i64_i32 v[0:1], s[0:1], v148, s48, v[0:1]
	v_mad_i64_i32 v[8:9], s[6:7], v19, s48, v[6:7]
	v_mad_i64_i32 v[6:7], s[6:7], v2, s48, v[6:7]
	v_lshl_add_u64 v[14:15], v[0:1], 0, s[22:23]
	v_lshlrev_b32_e32 v2, 4, v219
	v_lshl_add_u64 v[14:15], v[14:15], 0, v[2:3]
	s_mov_b64 s[0:1], 0x1400
	v_lshl_add_u64 v[16:17], v[14:15], 0, s[0:1]
	s_movk_i32 s0, 0x1000
	v_add_co_u32_e32 v14, vcc, s0, v14
	s_mov_b32 s0, 0x70000
	s_nop 0
	v_addc_co_u32_e32 v15, vcc, 0, v15, vcc
	global_load_dwordx4 v[100:103], v[8:9], off
	global_load_dwordx4 v[104:107], v[6:7], off
	v_add_co_u32_e32 v8, vcc, s0, v8
	global_load_dwordx4 v[112:115], v[10:11], off
	global_load_dwordx4 v[128:131], v[12:13], off
	v_addc_co_u32_e32 v9, vcc, 0, v9, vcc
	v_add_co_u32_e32 v6, vcc, s0, v6
	global_load_dwordx4 v[108:111], v[16:17], off offset:32
	global_load_dwordx4 v[116:119], v[16:17], off offset:64
	global_load_dwordx4 v[120:123], v[14:15], off offset:1024
	global_load_dwordx4 v[124:127], v[16:17], off offset:96
	v_addc_co_u32_e32 v7, vcc, 0, v7, vcc
	global_load_dwordx4 v[132:135], v[8:9], off
	global_load_dwordx4 v[136:139], v[6:7], off
	v_add_co_u32_e32 v6, vcc, s0, v10
	v_mul_u32_u24_e32 v5, 0x48, v5
	s_nop 0
	v_addc_co_u32_e32 v7, vcc, 0, v11, vcc
	v_add_co_u32_e32 v8, vcc, s0, v12
	s_movk_i32 s0, 0x90
	s_nop 0
	v_addc_co_u32_e32 v9, vcc, 0, v13, vcc
	global_load_dwordx4 v[140:143], v[6:7], off
	global_load_dwordx4 v[144:147], v[8:9], off
	v_lshrrev_b32_e32 v6, 3, v18
	v_bfe_u32 v7, v18, 2, 2
	v_mul_lo_u32 v9, v19, s0
	v_and_b32_e32 v8, 16, v18
	v_and_or_b32 v6, v6, 4, v7
	v_add3_u32 v239, 32, v9, v4
	v_lshlrev_b32_e32 v4, 2, v18
	v_lshlrev_b32_e32 v5, 1, v5
	v_and_or_b32 v4, v4, 12, v8
	v_add3_u32 v240, 32, v5, v2
	v_mul_u32_u24_e32 v5, 0x48, v6
	v_lshlrev_b32_e32 v4, 1, v4
	v_lshlrev_b32_e32 v5, 1, v5
	v_add3_u32 v241, 32, v4, v5
	v_add3_u32 v242, 32, v5, v4
	v_mad_i64_i32 v[4:5], s[0:1], v19, s48, 0
	v_mad_i64_i32 v[4:5], s[0:1], s36, v237, v[4:5]
	s_and_b32 s0, s4, 3
	v_and_b32_e32 v6, 7, v18
	s_lshl_b32 s0, s0, 7
	v_lshlrev_b32_e32 v6, 4, v6
	v_or3_b32 v4, v4, s0, v6
	v_mov_b32_e32 v18, v3
	v_mov_b32_e32 v19, v3
	v_lshl_add_u64 v[150:151], s[30:31], 0, v[4:5]
	v_mov_b32_e32 v4, v3
	v_mov_b32_e32 v5, v3
	v_mov_b32_e32 v6, v3
	v_mov_b32_e32 v7, v3
	v_mov_b32_e32 v8, v3
	v_mov_b32_e32 v9, v3
	v_mov_b32_e32 v10, v3
	v_mov_b32_e32 v11, v3
	v_mov_b32_e32 v12, v3
	v_mov_b32_e32 v13, v3
	v_mov_b32_e32 v14, v3
	v_mov_b32_e32 v15, v3
	v_mov_b32_e32 v16, v3
	v_mov_b32_e32 v17, v3
	s_waitcnt vmcnt(22)
	v_mov_b64_e32 v[34:35], v[18:19]
	s_waitcnt vmcnt(20)
	v_mov_b64_e32 v[66:67], v[18:19]
	v_mov_b64_e32 v[50:51], v[18:19]
	s_mov_b32 s39, 0
	v_ashrrev_i32_e32 v149, 31, v148
	v_mov_b32_e32 v153, 0
	s_mov_b64 s[0:1], 0
	v_mov_b64_e32 v[32:33], v[16:17]
	v_mov_b64_e32 v[30:31], v[14:15]
	v_mov_b64_e32 v[28:29], v[12:13]
	v_mov_b64_e32 v[26:27], v[10:11]
	v_mov_b64_e32 v[24:25], v[8:9]
	v_mov_b64_e32 v[22:23], v[6:7]
	v_mov_b64_e32 v[20:21], v[4:5]
	v_mov_b32_e32 v152, 0
	v_mov_b32_e32 v243, 0
	v_mov_b32_e32 v244, 0
	v_mov_b64_e32 v[64:65], v[16:17]
	v_mov_b64_e32 v[62:63], v[14:15]
	v_mov_b64_e32 v[60:61], v[12:13]
	v_mov_b64_e32 v[58:59], v[10:11]
	v_mov_b64_e32 v[56:57], v[8:9]
	v_mov_b64_e32 v[54:55], v[6:7]
	v_mov_b64_e32 v[52:53], v[4:5]
	v_mov_b64_e32 v[48:49], v[16:17]
	v_mov_b64_e32 v[46:47], v[14:15]
	v_mov_b64_e32 v[44:45], v[12:13]
	v_mov_b64_e32 v[42:43], v[10:11]
	v_mov_b64_e32 v[40:41], v[8:9]
	v_mov_b64_e32 v[38:39], v[6:7]
	v_mov_b64_e32 v[36:37], v[4:5]
	s_barrier
	s_waitcnt vmcnt(11)
	ds_write_b128 v239, v[100:103]
	s_waitcnt vmcnt(10)
	ds_write_b128 v239, v[104:107] offset:4608
	s_waitcnt vmcnt(9)
	ds_write_b128 v239, v[112:115] offset:18432
	s_waitcnt vmcnt(8)
	ds_write_b128 v239, v[128:131] offset:23040
	s_waitcnt lgkmcnt(0)
	s_barrier
	v_mov_b32_e32 v245, v239
	v_mov_b32_e32 v224, 0
	v_mov_b32_e32 v225, 0
	v_mov_b32_e32 v226, 0
	v_mov_b32_e32 v227, 0
	v_mov_b32_e32 v228, 0
	v_mov_b32_e32 v229, 0
	v_mov_b32_e32 v230, 0
	v_mov_b32_e32 v231, 0
	v_mov_b32_e32 v232, 0
	v_mov_b32_e32 v233, 0
	v_mov_b32_e32 v234, 0
	v_mov_b32_e32 v235, 0
	v_mov_b32_e32 v236, 0
	v_mov_b32_e32 v237, 0
	v_mov_b32_e32 v238, 0
	v_mov_b32_e32 v239, 0
	v_mov_b32_e32 v220, 0
	v_mov_b32_e32 v221, 0
	v_mov_b32_e32 v246, 0
	v_mov_b32_e32 v247, 0
.LBB0_766:
	s_add_i32 s22, s39, 2
	s_cmp_lt_u32 s22, s38
	s_cselect_b64 s[10:11], -1, 0
	s_cmp_ge_u32 s22, s38
	s_cselect_b64 s[12:13], -1, 0
	v_lshl_add_u64 v[254:255], v[150:151], 0, s[0:1]
	s_and_b64 vcc, exec, s[12:13]
	s_cbranch_vccnz .Lat_noload_a
	s_mov_b32 s4, 0x7275000
	s_mov_b32 s5, 0
	s_mov_b32 s6, 0x72ad000
	s_mov_b32 s7, 0
	v_lshl_add_u64 v[248:249], v[254:255], 0, s[4:5]
	v_lshl_add_u64 v[250:251], v[254:255], 0, s[6:7]
	global_load_dwordx4 v[100:103], v[248:249], off offset:1536
	global_load_dwordx4 v[112:115], v[248:249], off offset:2048
	global_load_dwordx4 v[104:107], v[250:251], off offset:1536
	global_load_dwordx4 v[128:131], v[250:251], off offset:2048
.Lat_noload_a:
	ds_read_b128 v[186:189], v240
	ds_read_b128 v[190:193], v240 offset:4608
	ds_read_b128 v[194:197], v240 offset:32
	ds_read_b128 v[198:201], v240 offset:4640
	ds_read_b128 v[202:205], v240 offset:64
	ds_read_b128 v[206:209], v240 offset:4672
	ds_read_b128 v[210:213], v240 offset:96
	ds_read_b128 v[214:217], v240 offset:4704
	s_waitcnt vmcnt(8) lgkmcnt(0)
	v_mfma_f32_32x32x16_bf16 v[68:83], v[186:189], v[120:123], v[224:239]
	ds_read_b64_tr_b16 v[186:187], v241 offset:18432
	ds_read_b64_tr_b16 v[188:189], v241 offset:19584
	v_mfma_f32_32x32x16_bf16 v[84:99], v[190:193], v[120:123], v[224:239]
	ds_read_b64_tr_b16 v[190:191], v241 offset:18496
	ds_read_b64_tr_b16 v[192:193], v241 offset:19648
	v_mfma_f32_32x32x16_bf16 v[68:83], v[194:197], v[108:111], v[68:83]
	ds_read_b64_tr_b16 v[194:195], v241 offset:20736
	ds_read_b64_tr_b16 v[196:197], v241 offset:21888
	v_mfma_f32_32x32x16_bf16 v[84:99], v[198:201], v[108:111], v[84:99]
	ds_read_b64_tr_b16 v[198:199], v241 offset:20800
	ds_read_b64_tr_b16 v[200:201], v241 offset:21952
	v_mfma_f32_32x32x16_bf16 v[154:169], v[202:205], v[116:119], v[224:239]
	ds_read_b64_tr_b16 v[202:203], v242 offset:23040
	ds_read_b64_tr_b16 v[204:205], v242 offset:24192
	v_mfma_f32_32x32x16_bf16 v[170:185], v[206:209], v[116:119], v[224:239]
	ds_read_b64_tr_b16 v[206:207], v242 offset:23104
	ds_read_b64_tr_b16 v[208:209], v242 offset:24256
	v_mfma_f32_32x32x16_bf16 v[154:169], v[210:213], v[124:127], v[154:169]
	ds_read_b64_tr_b16 v[210:211], v242 offset:25344
	ds_read_b64_tr_b16 v[212:213], v242 offset:26496
	v_mfma_f32_32x32x16_bf16 v[170:185], v[214:217], v[124:127], v[170:185]
	ds_read_b64_tr_b16 v[214:215], v242 offset:25408
	ds_read_b64_tr_b16 v[216:217], v242 offset:26560
	v_exp_f32_e32 v68, v68
	v_exp_f32_e32 v69, v69
	v_exp_f32_e32 v70, v70
	v_exp_f32_e32 v71, v71
	v_exp_f32_e32 v72, v72
	v_exp_f32_e32 v73, v73
	v_exp_f32_e32 v74, v74
	v_exp_f32_e32 v75, v75
	v_pk_add_f32 v[220:221], v[68:69], v[220:221]
	v_pk_add_f32 v[220:221], v[70:71], v[220:221]
	v_pk_add_f32 v[220:221], v[72:73], v[220:221]
	v_pk_add_f32 v[220:221], v[74:75], v[220:221]
	v_cvt_pk_bf16_f32 v68, v68, v69
	v_cvt_pk_bf16_f32 v69, v70, v71
	v_cvt_pk_bf16_f32 v70, v72, v73
	v_cvt_pk_bf16_f32 v71, v74, v75
	s_waitcnt lgkmcnt(12)
	s_nop 0
	v_mfma_f32_32x32x16_bf16 v[4:19], v[186:189], v[68:71], v[4:19]
	v_mfma_f32_32x32x16_bf16 v[20:35], v[190:193], v[68:71], v[20:35]
	v_exp_f32_e32 v154, v154
	v_exp_f32_e32 v155, v155
	v_exp_f32_e32 v156, v156
	v_exp_f32_e32 v157, v157
	v_exp_f32_e32 v158, v158
	v_exp_f32_e32 v159, v159
	v_exp_f32_e32 v160, v160
	v_exp_f32_e32 v161, v161
	v_pk_add_f32 v[246:247], v[154:155], v[246:247]
	v_pk_add_f32 v[246:247], v[156:157], v[246:247]
	v_pk_add_f32 v[246:247], v[158:159], v[246:247]
	v_pk_add_f32 v[246:247], v[160:161], v[246:247]
	v_cvt_pk_bf16_f32 v154, v154, v155
	v_cvt_pk_bf16_f32 v155, v156, v157
	v_cvt_pk_bf16_f32 v156, v158, v159
	v_cvt_pk_bf16_f32 v157, v160, v161
	s_nop 1
	v_mfma_f32_32x32x16_bf16 v[36:51], v[186:189], v[154:157], v[36:51]
	v_mfma_f32_32x32x16_bf16 v[52:67], v[190:193], v[154:157], v[52:67]
	v_exp_f32_e32 v76, v76
	v_exp_f32_e32 v77, v77
	v_exp_f32_e32 v78, v78
	v_exp_f32_e32 v79, v79
	v_exp_f32_e32 v80, v80
	v_exp_f32_e32 v81, v81
	v_exp_f32_e32 v82, v82
	v_exp_f32_e32 v83, v83
	v_pk_add_f32 v[220:221], v[76:77], v[220:221]
	v_pk_add_f32 v[220:221], v[78:79], v[220:221]
	v_pk_add_f32 v[220:221], v[80:81], v[220:221]
	v_pk_add_f32 v[220:221], v[82:83], v[220:221]
	v_cvt_pk_bf16_f32 v76, v76, v77
	v_cvt_pk_bf16_f32 v77, v78, v79
	v_cvt_pk_bf16_f32 v78, v80, v81
	v_cvt_pk_bf16_f32 v79, v82, v83
	s_waitcnt lgkmcnt(8)
	s_nop 0
	v_mfma_f32_32x32x16_bf16 v[4:19], v[194:197], v[76:79], v[4:19]
	v_mfma_f32_32x32x16_bf16 v[20:35], v[198:201], v[76:79], v[20:35]
	v_exp_f32_e32 v162, v162
	v_exp_f32_e32 v163, v163
	v_exp_f32_e32 v164, v164
	v_exp_f32_e32 v165, v165
	v_exp_f32_e32 v166, v166
	v_exp_f32_e32 v167, v167
	v_exp_f32_e32 v168, v168
	v_exp_f32_e32 v169, v169
	v_pk_add_f32 v[246:247], v[162:163], v[246:247]
	v_pk_add_f32 v[246:247], v[164:165], v[246:247]
	v_pk_add_f32 v[246:247], v[166:167], v[246:247]
	v_pk_add_f32 v[246:247], v[168:169], v[246:247]
	v_cvt_pk_bf16_f32 v162, v162, v163
	v_cvt_pk_bf16_f32 v163, v164, v165
	v_cvt_pk_bf16_f32 v164, v166, v167
	v_cvt_pk_bf16_f32 v165, v168, v169
	s_nop 1
	v_mfma_f32_32x32x16_bf16 v[36:51], v[194:197], v[162:165], v[36:51]
	v_mfma_f32_32x32x16_bf16 v[52:67], v[198:201], v[162:165], v[52:67]
	v_exp_f32_e32 v84, v84
	v_exp_f32_e32 v85, v85
	v_exp_f32_e32 v86, v86
	v_exp_f32_e32 v87, v87
	v_exp_f32_e32 v88, v88
	v_exp_f32_e32 v89, v89
	v_exp_f32_e32 v90, v90
	v_exp_f32_e32 v91, v91
	v_pk_add_f32 v[220:221], v[84:85], v[220:221]
	v_pk_add_f32 v[220:221], v[86:87], v[220:221]
	v_pk_add_f32 v[220:221], v[88:89], v[220:221]
	v_pk_add_f32 v[220:221], v[90:91], v[220:221]
	v_cvt_pk_bf16_f32 v84, v84, v85
	v_cvt_pk_bf16_f32 v85, v86, v87
	v_cvt_pk_bf16_f32 v86, v88, v89
	v_cvt_pk_bf16_f32 v87, v90, v91
	s_waitcnt lgkmcnt(4)
	s_nop 0
	v_mfma_f32_32x32x16_bf16 v[4:19], v[202:205], v[84:87], v[4:19]
	v_mfma_f32_32x32x16_bf16 v[20:35], v[206:209], v[84:87], v[20:35]
	v_exp_f32_e32 v170, v170
	v_exp_f32_e32 v171, v171
	v_exp_f32_e32 v172, v172
	v_exp_f32_e32 v173, v173
	v_exp_f32_e32 v174, v174
	v_exp_f32_e32 v175, v175
	v_exp_f32_e32 v176, v176
	v_exp_f32_e32 v177, v177
	v_pk_add_f32 v[246:247], v[170:171], v[246:247]
	v_pk_add_f32 v[246:247], v[172:173], v[246:247]
	v_pk_add_f32 v[246:247], v[174:175], v[246:247]
	v_pk_add_f32 v[246:247], v[176:177], v[246:247]
	v_cvt_pk_bf16_f32 v170, v170, v171
	v_cvt_pk_bf16_f32 v171, v172, v173
	v_cvt_pk_bf16_f32 v172, v174, v175
	v_cvt_pk_bf16_f32 v173, v176, v177
	s_nop 1
	v_mfma_f32_32x32x16_bf16 v[36:51], v[202:205], v[170:173], v[36:51]
	v_mfma_f32_32x32x16_bf16 v[52:67], v[206:209], v[170:173], v[52:67]
	v_exp_f32_e32 v92, v92
	v_exp_f32_e32 v93, v93
	v_exp_f32_e32 v94, v94
	v_exp_f32_e32 v95, v95
	v_exp_f32_e32 v96, v96
	v_exp_f32_e32 v97, v97
	v_exp_f32_e32 v98, v98
	v_exp_f32_e32 v99, v99
	v_pk_add_f32 v[220:221], v[92:93], v[220:221]
	v_pk_add_f32 v[220:221], v[94:95], v[220:221]
	v_pk_add_f32 v[220:221], v[96:97], v[220:221]
	v_pk_add_f32 v[220:221], v[98:99], v[220:221]
	v_cvt_pk_bf16_f32 v92, v92, v93
	v_cvt_pk_bf16_f32 v93, v94, v95
	v_cvt_pk_bf16_f32 v94, v96, v97
	v_cvt_pk_bf16_f32 v95, v98, v99
	s_waitcnt lgkmcnt(0)
	s_nop 0
	v_mfma_f32_32x32x16_bf16 v[4:19], v[210:213], v[92:95], v[4:19]
	v_mfma_f32_32x32x16_bf16 v[20:35], v[214:217], v[92:95], v[20:35]
	v_exp_f32_e32 v178, v178
	v_exp_f32_e32 v179, v179
	v_exp_f32_e32 v180, v180
	v_exp_f32_e32 v181, v181
	v_exp_f32_e32 v182, v182
	v_exp_f32_e32 v183, v183
	v_exp_f32_e32 v184, v184
	v_exp_f32_e32 v185, v185
	v_pk_add_f32 v[246:247], v[178:179], v[246:247]
	v_pk_add_f32 v[246:247], v[180:181], v[246:247]
	v_pk_add_f32 v[246:247], v[182:183], v[246:247]
	v_pk_add_f32 v[246:247], v[184:185], v[246:247]
	v_cvt_pk_bf16_f32 v178, v178, v179
	v_cvt_pk_bf16_f32 v179, v180, v181
	v_cvt_pk_bf16_f32 v180, v182, v183
	v_cvt_pk_bf16_f32 v181, v184, v185
	s_nop 1
	v_mfma_f32_32x32x16_bf16 v[36:51], v[210:213], v[178:181], v[36:51]
	v_mfma_f32_32x32x16_bf16 v[52:67], v[214:217], v[178:181], v[52:67]
	v_max3_f32 v248, v220, v221, v246
	v_max_f32_e32 v248, v248, v247
	v_cmp_lt_f32_e32 vcc, 0x49800000, v248
	s_cbranch_vccz .Lat_norescale_a
	v_add_f32_e32 v250, v220, v221
	v_add_f32_e32 v251, v246, v247
	v_lshlrev_b32_e32 v249, 2, v222
	v_xor_b32_e32 v249, 0x80, v249
	v_and_b32_e32 v249, 0xfc, v249
	ds_bpermute_b32 v68, v249, v250
	ds_bpermute_b32 v69, v249, v251
	s_waitcnt lgkmcnt(0)
	v_add_f32_e32 v250, v250, v68
	v_add_f32_e32 v251, v251, v69
	v_max_f32_e32 v250, v250, v251
	v_log_f32_e32 v250, v250
	s_nop 0
	v_max_f32_e32 v250, 0, v250
	v_add_f32_e32 v244, v244, v250
	v_exp_f32_e64 v248, -v250
	v_xor_b32_e32 v224, 0x80000000, v244
	v_mov_b32_e32 v225, v224
	v_mov_b32_e32 v226, v224
	v_mov_b32_e32 v227, v224
	v_mov_b32_e32 v228, v224
	v_mov_b32_e32 v229, v224
	v_mov_b32_e32 v230, v224
	v_mov_b32_e32 v231, v224
	v_mov_b32_e32 v232, v224
	v_mov_b32_e32 v233, v224
	v_mov_b32_e32 v234, v224
	v_mov_b32_e32 v235, v224
	v_mov_b32_e32 v236, v224
	v_mov_b32_e32 v237, v224
	v_mov_b32_e32 v238, v224
	v_mov_b32_e32 v239, v224
	v_mul_f32_e32 v220, v220, v248
	v_mul_f32_e32 v221, v221, v248
	v_mul_f32_e32 v246, v246, v248
	v_mul_f32_e32 v247, v247, v248
	v_pk_mul_f32 v[4:5], v[4:5], v[248:249] op_sel_hi:[1,0]
	v_pk_mul_f32 v[6:7], v[6:7], v[248:249] op_sel_hi:[1,0]
	v_pk_mul_f32 v[8:9], v[8:9], v[248:249] op_sel_hi:[1,0]
	v_pk_mul_f32 v[10:11], v[10:11], v[248:249] op_sel_hi:[1,0]
	v_pk_mul_f32 v[12:13], v[12:13], v[248:249] op_sel_hi:[1,0]
	v_pk_mul_f32 v[14:15], v[14:15], v[248:249] op_sel_hi:[1,0]
	v_pk_mul_f32 v[16:17], v[16:17], v[248:249] op_sel_hi:[1,0]
	v_pk_mul_f32 v[18:19], v[18:19], v[248:249] op_sel_hi:[1,0]
	v_pk_mul_f32 v[20:21], v[20:21], v[248:249] op_sel_hi:[1,0]
	v_pk_mul_f32 v[22:23], v[22:23], v[248:249] op_sel_hi:[1,0]
	v_pk_mul_f32 v[24:25], v[24:25], v[248:249] op_sel_hi:[1,0]
	v_pk_mul_f32 v[26:27], v[26:27], v[248:249] op_sel_hi:[1,0]
	v_pk_mul_f32 v[28:29], v[28:29], v[248:249] op_sel_hi:[1,0]
	v_pk_mul_f32 v[30:31], v[30:31], v[248:249] op_sel_hi:[1,0]
	v_pk_mul_f32 v[32:33], v[32:33], v[248:249] op_sel_hi:[1,0]
	v_pk_mul_f32 v[34:35], v[34:35], v[248:249] op_sel_hi:[1,0]
	v_pk_mul_f32 v[36:37], v[36:37], v[248:249] op_sel_hi:[1,0]
	v_pk_mul_f32 v[38:39], v[38:39], v[248:249] op_sel_hi:[1,0]
	v_pk_mul_f32 v[40:41], v[40:41], v[248:249] op_sel_hi:[1,0]
	v_pk_mul_f32 v[42:43], v[42:43], v[248:249] op_sel_hi:[1,0]
	v_pk_mul_f32 v[44:45], v[44:45], v[248:249] op_sel_hi:[1,0]
	v_pk_mul_f32 v[46:47], v[46:47], v[248:249] op_sel_hi:[1,0]
	v_pk_mul_f32 v[48:49], v[48:49], v[248:249] op_sel_hi:[1,0]
	v_pk_mul_f32 v[50:51], v[50:51], v[248:249] op_sel_hi:[1,0]
	v_pk_mul_f32 v[52:53], v[52:53], v[248:249] op_sel_hi:[1,0]
	v_pk_mul_f32 v[54:55], v[54:55], v[248:249] op_sel_hi:[1,0]
	v_pk_mul_f32 v[56:57], v[56:57], v[248:249] op_sel_hi:[1,0]
	v_pk_mul_f32 v[58:59], v[58:59], v[248:249] op_sel_hi:[1,0]
	v_pk_mul_f32 v[60:61], v[60:61], v[248:249] op_sel_hi:[1,0]
	v_pk_mul_f32 v[62:63], v[62:63], v[248:249] op_sel_hi:[1,0]
	v_pk_mul_f32 v[64:65], v[64:65], v[248:249] op_sel_hi:[1,0]
	v_pk_mul_f32 v[66:67], v[66:67], v[248:249] op_sel_hi:[1,0]
.Lat_norescale_a:
	s_waitcnt vmcnt(0)
	ds_write_b128 v245, v[132:135] offset:9216
	ds_write_b128 v245, v[136:139] offset:13824
	ds_write_b128 v245, v[140:143] offset:27648
	ds_write_b128 v245, v[144:147] offset:32256
	s_add_i32 s4, s39, 3
	s_cmp_ge_u32 s4, s38
	s_waitcnt lgkmcnt(0)
	s_barrier
	s_cbranch_scc1 .Lat_noload_b
	s_mov_b32 s4, 0x72e5000
	s_mov_b32 s5, 0
	s_mov_b32 s6, 0x731d000
	s_mov_b32 s7, 0
	v_lshl_add_u64 v[248:249], v[254:255], 0, s[4:5]
	v_lshl_add_u64 v[250:251], v[254:255], 0, s[6:7]
	global_load_dwordx4 v[132:135], v[248:249], off offset:1536
	global_load_dwordx4 v[140:143], v[248:249], off offset:2048
	global_load_dwordx4 v[136:139], v[250:251], off offset:1536
	global_load_dwordx4 v[144:147], v[250:251], off offset:2048
.Lat_noload_b:
	ds_read_b128 v[186:189], v240 offset:9216
	ds_read_b128 v[190:193], v240 offset:13824
	ds_read_b128 v[194:197], v240 offset:9248
	ds_read_b128 v[198:201], v240 offset:13856
	ds_read_b128 v[202:205], v240 offset:9280
	ds_read_b128 v[206:209], v240 offset:13888
	ds_read_b128 v[210:213], v240 offset:9312
	ds_read_b128 v[214:217], v240 offset:13920
	s_waitcnt vmcnt(8) lgkmcnt(0)
	v_mfma_f32_32x32x16_bf16 v[68:83], v[186:189], v[120:123], v[224:239]
	ds_read_b64_tr_b16 v[186:187], v241 offset:27648
	ds_read_b64_tr_b16 v[188:189], v241 offset:28800
	v_mfma_f32_32x32x16_bf16 v[84:99], v[190:193], v[120:123], v[224:239]
	ds_read_b64_tr_b16 v[190:191], v241 offset:27712
	ds_read_b64_tr_b16 v[192:193], v241 offset:28864
	v_mfma_f32_32x32x16_bf16 v[68:83], v[194:197], v[108:111], v[68:83]
	ds_read_b64_tr_b16 v[194:195], v241 offset:29952
	ds_read_b64_tr_b16 v[196:197], v241 offset:31104
	v_mfma_f32_32x32x16_bf16 v[84:99], v[198:201], v[108:111], v[84:99]
	ds_read_b64_tr_b16 v[198:199], v241 offset:30016
	ds_read_b64_tr_b16 v[200:201], v241 offset:31168
	v_mfma_f32_32x32x16_bf16 v[154:169], v[202:205], v[116:119], v[224:239]
	ds_read_b64_tr_b16 v[202:203], v242 offset:32256
	ds_read_b64_tr_b16 v[204:205], v242 offset:33408
	v_mfma_f32_32x32x16_bf16 v[170:185], v[206:209], v[116:119], v[224:239]
	ds_read_b64_tr_b16 v[206:207], v242 offset:32320
	ds_read_b64_tr_b16 v[208:209], v242 offset:33472
	v_mfma_f32_32x32x16_bf16 v[154:169], v[210:213], v[124:127], v[154:169]
	ds_read_b64_tr_b16 v[210:211], v242 offset:34560
	ds_read_b64_tr_b16 v[212:213], v242 offset:35712
	v_mfma_f32_32x32x16_bf16 v[170:185], v[214:217], v[124:127], v[170:185]
	ds_read_b64_tr_b16 v[214:215], v242 offset:34624
	ds_read_b64_tr_b16 v[216:217], v242 offset:35776
	v_exp_f32_e32 v68, v68
	v_exp_f32_e32 v69, v69
	v_exp_f32_e32 v70, v70
	v_exp_f32_e32 v71, v71
	v_exp_f32_e32 v72, v72
	v_exp_f32_e32 v73, v73
	v_exp_f32_e32 v74, v74
	v_exp_f32_e32 v75, v75
	v_pk_add_f32 v[220:221], v[68:69], v[220:221]
	v_pk_add_f32 v[220:221], v[70:71], v[220:221]
	v_pk_add_f32 v[220:221], v[72:73], v[220:221]
	v_pk_add_f32 v[220:221], v[74:75], v[220:221]
	v_cvt_pk_bf16_f32 v68, v68, v69
	v_cvt_pk_bf16_f32 v69, v70, v71
	v_cvt_pk_bf16_f32 v70, v72, v73
	v_cvt_pk_bf16_f32 v71, v74, v75
	s_waitcnt lgkmcnt(12)
	s_nop 0
	v_mfma_f32_32x32x16_bf16 v[4:19], v[186:189], v[68:71], v[4:19]
	v_mfma_f32_32x32x16_bf16 v[20:35], v[190:193], v[68:71], v[20:35]
	v_exp_f32_e32 v154, v154
	v_exp_f32_e32 v155, v155
	v_exp_f32_e32 v156, v156
	v_exp_f32_e32 v157, v157
	v_exp_f32_e32 v158, v158
	v_exp_f32_e32 v159, v159
	v_exp_f32_e32 v160, v160
	v_exp_f32_e32 v161, v161
	v_pk_add_f32 v[246:247], v[154:155], v[246:247]
	v_pk_add_f32 v[246:247], v[156:157], v[246:247]
	v_pk_add_f32 v[246:247], v[158:159], v[246:247]
	v_pk_add_f32 v[246:247], v[160:161], v[246:247]
	v_cvt_pk_bf16_f32 v154, v154, v155
	v_cvt_pk_bf16_f32 v155, v156, v157
	v_cvt_pk_bf16_f32 v156, v158, v159
	v_cvt_pk_bf16_f32 v157, v160, v161
	s_nop 1
	v_mfma_f32_32x32x16_bf16 v[36:51], v[186:189], v[154:157], v[36:51]
	v_mfma_f32_32x32x16_bf16 v[52:67], v[190:193], v[154:157], v[52:67]
	v_exp_f32_e32 v76, v76
	v_exp_f32_e32 v77, v77
	v_exp_f32_e32 v78, v78
	v_exp_f32_e32 v79, v79
	v_exp_f32_e32 v80, v80
	v_exp_f32_e32 v81, v81
	v_exp_f32_e32 v82, v82
	v_exp_f32_e32 v83, v83
	v_pk_add_f32 v[220:221], v[76:77], v[220:221]
	v_pk_add_f32 v[220:221], v[78:79], v[220:221]
	v_pk_add_f32 v[220:221], v[80:81], v[220:221]
	v_pk_add_f32 v[220:221], v[82:83], v[220:221]
	v_cvt_pk_bf16_f32 v76, v76, v77
	v_cvt_pk_bf16_f32 v77, v78, v79
	v_cvt_pk_bf16_f32 v78, v80, v81
	v_cvt_pk_bf16_f32 v79, v82, v83
	s_waitcnt lgkmcnt(8)
	s_nop 0
	v_mfma_f32_32x32x16_bf16 v[4:19], v[194:197], v[76:79], v[4:19]
	v_mfma_f32_32x32x16_bf16 v[20:35], v[198:201], v[76:79], v[20:35]
	v_exp_f32_e32 v162, v162
	v_exp_f32_e32 v163, v163
	v_exp_f32_e32 v164, v164
	v_exp_f32_e32 v165, v165
	v_exp_f32_e32 v166, v166
	v_exp_f32_e32 v167, v167
	v_exp_f32_e32 v168, v168
	v_exp_f32_e32 v169, v169
	v_pk_add_f32 v[246:247], v[162:163], v[246:247]
	v_pk_add_f32 v[246:247], v[164:165], v[246:247]
	v_pk_add_f32 v[246:247], v[166:167], v[246:247]
	v_pk_add_f32 v[246:247], v[168:169], v[246:247]
	v_cvt_pk_bf16_f32 v162, v162, v163
	v_cvt_pk_bf16_f32 v163, v164, v165
	v_cvt_pk_bf16_f32 v164, v166, v167
	v_cvt_pk_bf16_f32 v165, v168, v169
	s_nop 1
	v_mfma_f32_32x32x16_bf16 v[36:51], v[194:197], v[162:165], v[36:51]
	v_mfma_f32_32x32x16_bf16 v[52:67], v[198:201], v[162:165], v[52:67]
	v_exp_f32_e32 v84, v84
	v_exp_f32_e32 v85, v85
	v_exp_f32_e32 v86, v86
	v_exp_f32_e32 v87, v87
	v_exp_f32_e32 v88, v88
	v_exp_f32_e32 v89, v89
	v_exp_f32_e32 v90, v90
	v_exp_f32_e32 v91, v91
	v_pk_add_f32 v[220:221], v[84:85], v[220:221]
	v_pk_add_f32 v[220:221], v[86:87], v[220:221]
	v_pk_add_f32 v[220:221], v[88:89], v[220:221]
	v_pk_add_f32 v[220:221], v[90:91], v[220:221]
	v_cvt_pk_bf16_f32 v84, v84, v85
	v_cvt_pk_bf16_f32 v85, v86, v87
	v_cvt_pk_bf16_f32 v86, v88, v89
	v_cvt_pk_bf16_f32 v87, v90, v91
	s_waitcnt lgkmcnt(4)
	s_nop 0
	v_mfma_f32_32x32x16_bf16 v[4:19], v[202:205], v[84:87], v[4:19]
	v_mfma_f32_32x32x16_bf16 v[20:35], v[206:209], v[84:87], v[20:35]
	v_exp_f32_e32 v170, v170
	v_exp_f32_e32 v171, v171
	v_exp_f32_e32 v172, v172
	v_exp_f32_e32 v173, v173
	v_exp_f32_e32 v174, v174
	v_exp_f32_e32 v175, v175
	v_exp_f32_e32 v176, v176
	v_exp_f32_e32 v177, v177
	v_pk_add_f32 v[246:247], v[170:171], v[246:247]
	v_pk_add_f32 v[246:247], v[172:173], v[246:247]
	v_pk_add_f32 v[246:247], v[174:175], v[246:247]
	v_pk_add_f32 v[246:247], v[176:177], v[246:247]
	v_cvt_pk_bf16_f32 v170, v170, v171
	v_cvt_pk_bf16_f32 v171, v172, v173
	v_cvt_pk_bf16_f32 v172, v174, v175
	v_cvt_pk_bf16_f32 v173, v176, v177
	s_nop 1
	v_mfma_f32_32x32x16_bf16 v[36:51], v[202:205], v[170:173], v[36:51]
	v_mfma_f32_32x32x16_bf16 v[52:67], v[206:209], v[170:173], v[52:67]
	v_exp_f32_e32 v92, v92
	v_exp_f32_e32 v93, v93
	v_exp_f32_e32 v94, v94
	v_exp_f32_e32 v95, v95
	v_exp_f32_e32 v96, v96
	v_exp_f32_e32 v97, v97
	v_exp_f32_e32 v98, v98
	v_exp_f32_e32 v99, v99
	v_pk_add_f32 v[220:221], v[92:93], v[220:221]
	v_pk_add_f32 v[220:221], v[94:95], v[220:221]
	v_pk_add_f32 v[220:221], v[96:97], v[220:221]
	v_pk_add_f32 v[220:221], v[98:99], v[220:221]
	v_cvt_pk_bf16_f32 v92, v92, v93
	v_cvt_pk_bf16_f32 v93, v94, v95
	v_cvt_pk_bf16_f32 v94, v96, v97
	v_cvt_pk_bf16_f32 v95, v98, v99
	s_waitcnt lgkmcnt(0)
	s_nop 0
	v_mfma_f32_32x32x16_bf16 v[4:19], v[210:213], v[92:95], v[4:19]
	v_mfma_f32_32x32x16_bf16 v[20:35], v[214:217], v[92:95], v[20:35]
	v_exp_f32_e32 v178, v178
	v_exp_f32_e32 v179, v179
	v_exp_f32_e32 v180, v180
	v_exp_f32_e32 v181, v181
	v_exp_f32_e32 v182, v182
	v_exp_f32_e32 v183, v183
	v_exp_f32_e32 v184, v184
	v_exp_f32_e32 v185, v185
	v_pk_add_f32 v[246:247], v[178:179], v[246:247]
	v_pk_add_f32 v[246:247], v[180:181], v[246:247]
	v_pk_add_f32 v[246:247], v[182:183], v[246:247]
	v_pk_add_f32 v[246:247], v[184:185], v[246:247]
	v_cvt_pk_bf16_f32 v178, v178, v179
	v_cvt_pk_bf16_f32 v179, v180, v181
	v_cvt_pk_bf16_f32 v180, v182, v183
	v_cvt_pk_bf16_f32 v181, v184, v185
	s_nop 1
	v_mfma_f32_32x32x16_bf16 v[36:51], v[210:213], v[178:181], v[36:51]
	v_mfma_f32_32x32x16_bf16 v[52:67], v[214:217], v[178:181], v[52:67]
	v_max3_f32 v248, v220, v221, v246
	v_max_f32_e32 v248, v248, v247
	v_cmp_lt_f32_e32 vcc, 0x49800000, v248
	s_cbranch_vccz .Lat_norescale_b
	v_add_f32_e32 v250, v220, v221
	v_add_f32_e32 v251, v246, v247
	v_lshlrev_b32_e32 v249, 2, v222
	v_xor_b32_e32 v249, 0x80, v249
	v_and_b32_e32 v249, 0xfc, v249
	ds_bpermute_b32 v68, v249, v250
	ds_bpermute_b32 v69, v249, v251
	s_waitcnt lgkmcnt(0)
	v_add_f32_e32 v250, v250, v68
	v_add_f32_e32 v251, v251, v69
	v_max_f32_e32 v250, v250, v251
	v_log_f32_e32 v250, v250
	s_nop 0
	v_max_f32_e32 v250, 0, v250
	v_add_f32_e32 v244, v244, v250
	v_exp_f32_e64 v248, -v250
	v_xor_b32_e32 v224, 0x80000000, v244
	v_mov_b32_e32 v225, v224
	v_mov_b32_e32 v226, v224
	v_mov_b32_e32 v227, v224
	v_mov_b32_e32 v228, v224
	v_mov_b32_e32 v229, v224
	v_mov_b32_e32 v230, v224
	v_mov_b32_e32 v231, v224
	v_mov_b32_e32 v232, v224
	v_mov_b32_e32 v233, v224
	v_mov_b32_e32 v234, v224
	v_mov_b32_e32 v235, v224
	v_mov_b32_e32 v236, v224
	v_mov_b32_e32 v237, v224
	v_mov_b32_e32 v238, v224
	v_mov_b32_e32 v239, v224
	v_mul_f32_e32 v220, v220, v248
	v_mul_f32_e32 v221, v221, v248
	v_mul_f32_e32 v246, v246, v248
	v_mul_f32_e32 v247, v247, v248
	v_pk_mul_f32 v[4:5], v[4:5], v[248:249] op_sel_hi:[1,0]
	v_pk_mul_f32 v[6:7], v[6:7], v[248:249] op_sel_hi:[1,0]
	v_pk_mul_f32 v[8:9], v[8:9], v[248:249] op_sel_hi:[1,0]
	v_pk_mul_f32 v[10:11], v[10:11], v[248:249] op_sel_hi:[1,0]
	v_pk_mul_f32 v[12:13], v[12:13], v[248:249] op_sel_hi:[1,0]
	v_pk_mul_f32 v[14:15], v[14:15], v[248:249] op_sel_hi:[1,0]
	v_pk_mul_f32 v[16:17], v[16:17], v[248:249] op_sel_hi:[1,0]
	v_pk_mul_f32 v[18:19], v[18:19], v[248:249] op_sel_hi:[1,0]
	v_pk_mul_f32 v[20:21], v[20:21], v[248:249] op_sel_hi:[1,0]
	v_pk_mul_f32 v[22:23], v[22:23], v[248:249] op_sel_hi:[1,0]
	v_pk_mul_f32 v[24:25], v[24:25], v[248:249] op_sel_hi:[1,0]
	v_pk_mul_f32 v[26:27], v[26:27], v[248:249] op_sel_hi:[1,0]
	v_pk_mul_f32 v[28:29], v[28:29], v[248:249] op_sel_hi:[1,0]
	v_pk_mul_f32 v[30:31], v[30:31], v[248:249] op_sel_hi:[1,0]
	v_pk_mul_f32 v[32:33], v[32:33], v[248:249] op_sel_hi:[1,0]
	v_pk_mul_f32 v[34:35], v[34:35], v[248:249] op_sel_hi:[1,0]
	v_pk_mul_f32 v[36:37], v[36:37], v[248:249] op_sel_hi:[1,0]
	v_pk_mul_f32 v[38:39], v[38:39], v[248:249] op_sel_hi:[1,0]
	v_pk_mul_f32 v[40:41], v[40:41], v[248:249] op_sel_hi:[1,0]
	v_pk_mul_f32 v[42:43], v[42:43], v[248:249] op_sel_hi:[1,0]
	v_pk_mul_f32 v[44:45], v[44:45], v[248:249] op_sel_hi:[1,0]
	v_pk_mul_f32 v[46:47], v[46:47], v[248:249] op_sel_hi:[1,0]
	v_pk_mul_f32 v[48:49], v[48:49], v[248:249] op_sel_hi:[1,0]
	v_pk_mul_f32 v[50:51], v[50:51], v[248:249] op_sel_hi:[1,0]
	v_pk_mul_f32 v[52:53], v[52:53], v[248:249] op_sel_hi:[1,0]
	v_pk_mul_f32 v[54:55], v[54:55], v[248:249] op_sel_hi:[1,0]
	v_pk_mul_f32 v[56:57], v[56:57], v[248:249] op_sel_hi:[1,0]
	v_pk_mul_f32 v[58:59], v[58:59], v[248:249] op_sel_hi:[1,0]
	v_pk_mul_f32 v[60:61], v[60:61], v[248:249] op_sel_hi:[1,0]
	v_pk_mul_f32 v[62:63], v[62:63], v[248:249] op_sel_hi:[1,0]
	v_pk_mul_f32 v[64:65], v[64:65], v[248:249] op_sel_hi:[1,0]
	v_pk_mul_f32 v[66:67], v[66:67], v[248:249] op_sel_hi:[1,0]
.Lat_norescale_b:
	s_andn2_b64 vcc, exec, s[10:11]
	s_cbranch_vccnz .Lat_nowrite_a
	s_waitcnt vmcnt(4)
	ds_write_b128 v245, v[100:103]
	ds_write_b128 v245, v[104:107] offset:4608
	ds_write_b128 v245, v[112:115] offset:18432
	ds_write_b128 v245, v[128:131] offset:23040
.Lat_nowrite_a:
	s_add_u32 s0, s0, 0xe0000
	s_addc_u32 s1, s1, 0
	s_andn2_b64 vcc, exec, s[12:13]
	s_waitcnt lgkmcnt(0)
	s_barrier
	s_cbranch_vccnz .Lat_more
	v_add_f32_e32 v152, v220, v221
	v_add_f32_e32 v153, v246, v247
	v_mov_b32_e32 v224, 0x1000
	v_mov_b32_e32 v225, 0x2000
	v_mov_b32_e32 v226, 1
	v_mov_b32_e32 v227, 0x3727c5ac
	v_mov_b32_e32 v228, 0x3ecc95a3
	v_bfrev_b32_e32 v229, 0.5
	v_mov_b32_e32 v230, 0x41b17218
	v_mov_b32_e32 v231, 0x3e8293ee
	v_mov_b32_e32 v232, 0xfffff000
	v_mov_b32_e32 v233, 0x1c00
	v_mov_b32_e32 v234, 0x7f800000
	v_mov_b32_e32 v235, 0x7fc00000
	v_mov_b32_e32 v236, 0xff800000
	v_mov_b32_e32 v237, 0x1dc0000
	v_mov_b32_e32 v238, 0x1100
	s_branch .LBB0_541
.Lat_more:
	s_mov_b32 s39, s22
	s_branch .LBB0_766

	.amdhsa_kernel _Z14fwd_megakernel6Params
		.amdhsa_group_segment_fixed_size 32
		.amdhsa_private_segment_fixed_size 0
		.amdhsa_kernarg_size 496
		.amdhsa_user_sgpr_count 2
		.amdhsa_user_sgpr_dispatch_ptr 0
		.amdhsa_user_sgpr_queue_ptr 0
		.amdhsa_user_sgpr_kernarg_segment_ptr 1
		.amdhsa_user_sgpr_dispatch_id 0
		.amdhsa_user_sgpr_kernarg_preload_length 0
		.amdhsa_user_sgpr_kernarg_preload_offset 0
		.amdhsa_user_sgpr_private_segment_size 0
		.amdhsa_uses_dynamic_stack 0
		.amdhsa_enable_private_segment 0
		.amdhsa_system_sgpr_workgroup_id_x 1
		.amdhsa_system_sgpr_workgroup_id_y 0
		.amdhsa_system_sgpr_workgroup_id_z 0
		.amdhsa_system_sgpr_workgroup_info 0
		.amdhsa_system_vgpr_workitem_id 2
		.amdhsa_next_free_vgpr 256
		.amdhsa_next_free_sgpr 100
		.amdhsa_accum_offset 256
		.amdhsa_reserve_vcc 1
		.amdhsa_float_round_mode_32 0
		.amdhsa_float_round_mode_16_64 0
		.amdhsa_float_denorm_mode_32 3
		.amdhsa_float_denorm_mode_16_64 3
		.amdhsa_dx10_clamp 1
		.amdhsa_ieee_mode 1
		.amdhsa_fp16_overflow 0
		.amdhsa_tg_split 0
		.amdhsa_exception_fp_ieee_invalid_op 0
		.amdhsa_exception_fp_denorm_src 0
		.amdhsa_exception_fp_ieee_div_zero 0
		.amdhsa_exception_fp_ieee_overflow 0
		.amdhsa_exception_fp_ieee_underflow 0
		.amdhsa_exception_fp_ieee_inexact 0
		.amdhsa_exception_int_div_zero 0
	.end_amdhsa_kernel

amdhsa.kernels:
  - .agpr_count:     0
    .args:
      - .offset:         0
        .size:           240
        .value_kind:     by_value
      - .offset:         240
        .size:           4
        .value_kind:     hidden_block_count_x
      - .offset:         244
        .size:           4
        .value_kind:     hidden_block_count_y
      - .offset:         248
        .size:           4
        .value_kind:     hidden_block_count_z
      - .offset:         252
        .size:           2
        .value_kind:     hidden_group_size_x
      - .offset:         254
        .size:           2
        .value_kind:     hidden_group_size_y
      - .offset:         256
        .size:           2
        .value_kind:     hidden_group_size_z
      - .offset:         258
        .size:           2
        .value_kind:     hidden_remainder_x
      - .offset:         260
        .size:           2
        .value_kind:     hidden_remainder_y
      - .offset:         262
        .size:           2
        .value_kind:     hidden_remainder_z
      - .offset:         280
        .size:           8
        .value_kind:     hidden_global_offset_x
      - .offset:         288
        .size:           8
        .value_kind:     hidden_global_offset_y
      - .offset:         296
        .size:           8
        .value_kind:     hidden_global_offset_z
      - .offset:         304
        .size:           2
        .value_kind:     hidden_grid_dims
      - .offset:         328
        .size:           8
        .value_kind:     hidden_multigrid_sync_arg
      - .offset:         360
        .size:           4
        .value_kind:     hidden_dynamic_lds_size
    .group_segment_fixed_size: 32
    .kernarg_segment_align: 8
    .kernarg_segment_size: 496
    .language:       OpenCL C
    .language_version:
      - 2
      - 0
    .max_flat_workgroup_size: 256
    .name:           _Z14fwd_megakernel6Params
    .private_segment_fixed_size: 0
    .sgpr_count:     106
    .sgpr_spill_count: 126
    .symbol:         _Z14fwd_megakernel6Params.kd
    .uniform_work_group_size: 1
    .uses_dynamic_stack: false
    .vgpr_count:     256
    .vgpr_spill_count: 0
    .wavefront_size: 64
